# v8 + one static s_setprio 1 for waves 4-7 for the whole attention phase (reset at its end)
# baseline (speedup 1.0000x reference)
; #define LAS __attribute__((address_space(3)))
; __global__ void __launch_bounds__(NTHREADS, 2) fwd_kernel(Args args) {
;     ...
;     if (IN(3)) for (int rep = 0; rep < NREP(3); ++rep) {
;         char* al = (char*)lds;
;         LAS float* FL = (LAS float*)(L + att::OFF_FL);
;         LAS float* TB = (LAS float*)(L + att::OFF_TB);
;         volatile LAS int* QW = (volatile LAS int*)(L + att::OFF_QW);
;         bf16* QAb = QKV; bf16* KAb = QKV + QKV_STRIDE; bf16* VAb = QKV + 2 * QKV_STRIDE; bf16* QBb = QKV + 3 * QKV_STRIDE; bf16* KBb = QKV + 4 * QKV_STRIDE; bf16* VBb = QKV + 5 * QKV_STRIDE;
;         unsigned char* OA8 = (unsigned char*)Hb; unsigned char* OB8 = OA8 + QKV_STRIDE_B;
;         const float* rel = arg_in(14);
;         att::Seam S;
;         if (vcu < 256) {
.LBB0_641:
	v_readlane_b32 s100, v255, 5
	s_nop 3
	s_cmp_lt_u32 s100, 4
	s_cbranch_scc1 .Lp3_prio_done
	s_setprio 1

; #define SEAM(k) do { if (IN(k) && IN((k) + 1)) xcd_barrier(bar, wave); } while (0)
; __global__ void __launch_bounds__(NTHREADS, 2) fwd_kernel(Args args) {
;     ...
;         __syncthreads();
;     ...
;     }
;     SEAM(3);
.LBB0_1985:
	s_setprio 0
	v_readlane_b32 s97, v255, 12
	s_barrier
